# finish and l=1 post phases: static s_setprio 1 for waves 4-7
# speedup vs baseline: 1.0039x; 1.0039x over previous
; DI void unpack8(u32x4 v, float* o) { o[0] = lo16(v.x); o[1] = hi16(v.x); o[2] = lo16(v.y); o[3] = hi16(v.y); o[4] = lo16(v.z); o[5] = hi16(v.z); o[6] = lo16(v.w); o[7] = hi16(v.w); }
; DI u32x4 pack8(const float* o) { u32x4 r; r.x = pk2(o[0], o[1]); r.y = pk2(o[2], o[3]); r.z = pk2(o[4], o[5]); r.w = pk2(o[6], o[7]); return r; }
; DI float siluf(float x) { return x * __builtin_amdgcn_rcpf(1.f + __expf(-x)); }
; DI int otid() { int t = threadIdx.x; asm volatile("" : "+v"(t)); return t; }
; DI void finish_item(const P& p, int l, int r16) {
;     const bf16_t* S = (const bf16_t*)(p.ws + WS_SBUF);
;     bf16_t* Y = (bf16_t*)(p.ws + WS_YBUF);
;     const bf16_t* O = (const bf16_t*)(p.ws + WS_NBUF);
;     const int tid = otid(); const int row0 = r16 * 16 + (tid >> 7) * 4, u = tid & 127, mx = u >> 6, hh = (u >> 4) & 3, sub = u & 15;
;     const int chn = 128 * hh + 8 * sub;
;     u32x4 ra[4], rb[4], rg[4];
; #pragma unroll
;     for (int k = 0; k < 4; ++k) {
;         ra[k] = __builtin_nontemporal_load((const u32x4*)(O + ((size_t)(mx * 2 + 0) * NROW + row0 + k) * 512 + chn));
;         rb[k] = __builtin_nontemporal_load((const u32x4*)(O + ((size_t)(mx * 2 + 1) * NROW + row0 + k) * 512 + chn));
;         rg[k] = __builtin_nontemporal_load((const u32x4*)(S + (size_t)(row0 + k) * NP + (mx ? C_GDN_G : C_GLA_G) + chn));
;     }
;     const float* nwp = (mx ? p.gdn_norm : p.gla_norm) + l * 128 + 8 * sub;
;     const f32x4 nw0 = *(const f32x4*)nwp, nw1 = *(const f32x4*)(nwp + 4);
; #pragma unroll
;     for (int k = 0; k < 4; ++k) {
;         float a[8], b[8], o[8], gt[8];
;         unpack8(ra[k], a); unpack8(rb[k], b); unpack8(rg[k], gt);
;         float ss = 0.f;
; #pragma unroll
;         for (int e = 0; e < 8; ++e) { o[e] = a[e] + b[e]; ss += o[e] * o[e]; }
;         ss += __shfl_xor(ss, 1); ss += __shfl_xor(ss, 2); ss += __shfl_xor(ss, 4); ss += __shfl_xor(ss, 8);
;         const float rstd = rsqrtf(ss * (1.f / 128.f) + 1e-6f);
; #pragma unroll
;         for (int e = 0; e < 8; ++e) o[e] = o[e] * rstd * (e < 4 ? nw0[e & 3] : nw1[e & 3]) * siluf(gt[e]);
;         *(u32x4*)(Y + (size_t)(row0 + k) * DM + 512 * mx + chn) = pack8(o);
;     }
; }
; __global__ __launch_bounds__(512, 2) void mega(P p) {
;     ...
;         { PHASE_BEGIN const int nf = (l == 0 ? NROW : NLAT) / 16; for (int it = b1; it < nf; it += nb) { ITEM_BEGIN finish_item(q, l, it); } }
.LBB0_679:
	s_or_b64 exec, exec, s[0:1]
	s_mov_b64 s[0:1], 0
	s_waitcnt lgkmcnt(0)
	s_barrier
	s_mov_b32 s0, s19
	v_readlane_b32 s4, v254, 26
	v_readlane_b32 s0, v252, 1
	v_readlane_b32 s1, v252, 2
	s_and_b64 s[0:1], s[0:1], exec
	s_movk_i32 s0, 0x240
	v_readlane_b32 s21, v253, 0
	s_cselect_b32 s22, s0, 0x200
	v_readlane_b32 s7, v254, 29
	v_readlane_b32 s36, v254, 39
	s_cmp_ge_i32 s21, s22
	v_readlane_b32 s5, v254, 27
	v_readlane_b32 s6, v254, 28
	s_movk_i32 s7, 0x3800
	s_mov_b64 s[8:9], 0x6c3c000
	s_brev_b32 s10, 60
	v_readlane_b32 s40, v254, 43
	v_readlane_b32 s41, v254, 44
	v_readlane_b32 s48, v254, 51
	v_readlane_b32 s49, v254, 52
	v_readlane_b32 s37, v254, 40
	v_readlane_b32 s38, v254, 41
	v_readlane_b32 s39, v254, 42
	v_readlane_b32 s42, v254, 45
	v_readlane_b32 s43, v254, 46
	v_readlane_b32 s44, v254, 47
	v_readlane_b32 s45, v254, 48
	v_readlane_b32 s46, v254, 49
	v_readlane_b32 s47, v254, 50
	v_readlane_b32 s50, v254, 53
	v_readlane_b32 s51, v254, 54
	s_cbranch_scc1 .LBB0_682
	v_readfirstlane_b32 s98, v166
	s_nop 0
	s_lshr_b32 s98, s98, 6
	s_cmp_ge_u32 s98, 4
	s_cbranch_scc0 .Lfin_prio_done
	s_setprio 1
.Lfin_prio_done:
	v_lshrrev_b32_e32 v118, 7, v166
	v_and_b32_e32 v119, 0x7f, v166
	v_lshrrev_b32_e32 v120, 6, v119
	v_and_b32_e32 v121, 63, v119
	v_lshlrev_b32_e32 v121, 4, v121
	v_lshlrev_b32_e32 v104, 24, v120
	v_lshl_add_u32 v104, v120, 21, v104
	v_lshl_add_u32 v104, v118, 10, v104
	v_add_u32_e32 v104, v104, v121
	v_add_u32_e32 v104, 0x483c000, v104
	v_add_u32_e32 v105, 0x900000, v104
	v_mul_u32_u24_e32 v106, 0x3800, v118
	v_lshl_add_u32 v106, v120, 12, v106
	v_add_u32_e32 v106, v106, v121
	v_add_u32_e32 v106, 0x6c3c800, v106
	v_lshlrev_b32_e32 v107, 12, v118
	v_lshl_add_u32 v107, v120, 10, v107
	v_add_u32_e32 v107, v107, v121
	v_add_u32_e32 v107, 0xea3c000, v107
	v_and_b32_e32 v123, 15, v119
	v_lshlrev_b32_e32 v123, 5, v123
	s_lshl_b32 s0, s12, 9
	v_add_u32_e32 v123, s0, v123
	v_cmp_eq_u32_e32 vcc, 0, v120
	s_and_saveexec_b64 s[2:3], vcc
	global_load_dwordx4 v[96:99], v123, s[40:41]
	global_load_dwordx4 v[100:103], v123, s[40:41] offset:16
	s_andn2_b64 exec, s[2:3], exec
	global_load_dwordx4 v[96:99], v123, s[48:49]
	global_load_dwordx4 v[100:103], v123, s[48:49] offset:16
	s_mov_b64 exec, s[2:3]
	v_mov_b32_e32 v124, 0x358637bd
	v_mov_b32_e32 v125, 0xbfb8aa3b
	s_lshl_b32 s10, s22, 2
	s_lshl_b32 s0, s6, 3
	s_add_u32 s0, s0, s21
	s_add_u32 s1, s0, s6
	s_cmp_lt_u32 s0, s10
	s_cbranch_scc0 .Lfin_generic
	s_cmp_lt_u32 s1, s10
	s_cbranch_scc1 .Lfin_generic
	s_mov_b32 s24, s21
	s_mov_b32 s7, s21
	s_lshl_b32 s0, s7, 12
	s_add_u32 s36, s4, s0
	s_addc_u32 s37, s5, 0
	s_mul_i32 s0, s7, 0xe000
	s_add_u32 s38, s4, s0
	s_addc_u32 s39, s5, 0
	global_load_dwordx4 v[0:3], v104, s[36:37] nt
	global_load_dwordx4 v[4:7], v105, s[36:37] nt
	global_load_dwordx4 v[8:11], v106, s[38:39] nt
	s_add_u32 s7, s7, s6
	s_lshl_b32 s0, s7, 12
	s_add_u32 s36, s4, s0
	s_addc_u32 s37, s5, 0
	s_mul_i32 s0, s7, 0xe000
	s_add_u32 s38, s4, s0
	s_addc_u32 s39, s5, 0
	global_load_dwordx4 v[12:15], v104, s[36:37] nt
	global_load_dwordx4 v[16:19], v105, s[36:37] nt
	global_load_dwordx4 v[20:23], v106, s[38:39] nt
	s_add_u32 s7, s7, s6
	s_lshl_b32 s0, s7, 12
	s_add_u32 s36, s4, s0
	s_addc_u32 s37, s5, 0
	s_mul_i32 s0, s7, 0xe000
	s_add_u32 s38, s4, s0
	s_addc_u32 s39, s5, 0
	global_load_dwordx4 v[24:27], v104, s[36:37] nt
	global_load_dwordx4 v[28:31], v105, s[36:37] nt
	global_load_dwordx4 v[32:35], v106, s[38:39] nt
	s_add_u32 s7, s7, s6
	s_lshl_b32 s0, s7, 12
	s_add_u32 s36, s4, s0
	s_addc_u32 s37, s5, 0
	s_mul_i32 s0, s7, 0xe000
	s_add_u32 s38, s4, s0
	s_addc_u32 s39, s5, 0
	global_load_dwordx4 v[36:39], v104, s[36:37] nt
	global_load_dwordx4 v[40:43], v105, s[36:37] nt
	global_load_dwordx4 v[44:47], v106, s[38:39] nt
	s_add_u32 s7, s7, s6
	s_waitcnt vmcnt(9)
	v_and_b32_e32 v118, 0xffff0000, v0
	v_and_b32_e32 v119, 0xffff0000, v4
	v_lshlrev_b32_e32 v0, 16, v0
	v_lshlrev_b32_e32 v120, 16, v4
	v_add_f32_e32 v0, v0, v120
	v_add_f32_e32 v4, v118, v119
	v_mul_f32_e32 v142, v0, v0
	v_fmac_f32_e32 v142, v4, v4
	v_and_b32_e32 v118, 0xffff0000, v1
	v_and_b32_e32 v119, 0xffff0000, v5
	v_lshlrev_b32_e32 v1, 16, v1
	v_lshlrev_b32_e32 v120, 16, v5
	v_add_f32_e32 v1, v1, v120
	v_add_f32_e32 v5, v118, v119
	v_fmac_f32_e32 v142, v1, v1
	v_fmac_f32_e32 v142, v5, v5
	v_and_b32_e32 v118, 0xffff0000, v2
	v_and_b32_e32 v119, 0xffff0000, v6
	v_lshlrev_b32_e32 v2, 16, v2
	v_lshlrev_b32_e32 v120, 16, v6
	v_add_f32_e32 v2, v2, v120
	v_add_f32_e32 v6, v118, v119
	v_fmac_f32_e32 v142, v2, v2
	v_fmac_f32_e32 v142, v6, v6
	v_and_b32_e32 v118, 0xffff0000, v3
	v_and_b32_e32 v119, 0xffff0000, v7
	v_lshlrev_b32_e32 v3, 16, v3
	v_lshlrev_b32_e32 v120, 16, v7
	v_add_f32_e32 v3, v3, v120
	v_add_f32_e32 v7, v118, v119
	v_fmac_f32_e32 v142, v3, v3
	v_fmac_f32_e32 v142, v7, v7
	s_nop 1
	v_add_f32_dpp v142, v142, v142 quad_perm:[1,0,3,2] row_mask:0xf bank_mask:0xf
	s_nop 1
	v_add_f32_dpp v142, v142, v142 quad_perm:[2,3,0,1] row_mask:0xf bank_mask:0xf
	s_nop 1
	v_add_f32_dpp v142, v142, v142 row_half_mirror row_mask:0xf bank_mask:0xf
	s_nop 1
	v_add_f32_dpp v142, v142, v142 row_mirror row_mask:0xf bank_mask:0xf
	v_fmamk_f32 v142, v142, 0x3c000000, v124
	v_rsq_f32_e32 v150, v142
	s_lshl_b32 s0, s24, 14
	s_add_u32 s42, s4, s0
	s_addc_u32 s43, s5, 0
	v_lshlrev_b32_e32 v118, 16, v8
	v_and_b32_e32 v119, 0xffff0000, v8
	v_mul_f32_e32 v120, v125, v118
	v_mul_f32_e32 v121, v125, v119
	v_exp_f32_e32 v120, v120
	v_exp_f32_e32 v121, v121
	v_mul_f32_e32 v0, v0, v150
	v_add_f32_e32 v120, 1.0, v120
	v_add_f32_e32 v121, 1.0, v121
	v_rcp_f32_e32 v120, v120
	v_rcp_f32_e32 v121, v121
	v_mul_f32_e32 v4, v4, v150
; DI void unpack8(u32x4 v, float* o) { o[0] = lo16(v.x); o[1] = hi16(v.x); o[2] = lo16(v.y); o[3] = hi16(v.y); o[4] = lo16(v.z); o[5] = hi16(v.z); o[6] = lo16(v.w); o[7] = hi16(v.w); }
; DI u32x4 pack8(const float* o) { u32x4 r; r.x = pk2(o[0], o[1]); r.y = pk2(o[2], o[3]); r.z = pk2(o[4], o[5]); r.w = pk2(o[6], o[7]); return r; }
; DI float siluf(float x) { return x * __builtin_amdgcn_rcpf(1.f + __expf(-x)); }
; DI void finish_item(const P& p, int l, int r16) {
;     ...
;     for (int k = 0; k < 4; ++k) {
;         float a[8], b[8], o[8], gt[8];
;         unpack8(ra[k], a); unpack8(rb[k], b); unpack8(rg[k], gt);
;         float ss = 0.f;
; #pragma unroll
;         for (int e = 0; e < 8; ++e) { o[e] = a[e] + b[e]; ss += o[e] * o[e]; }
;         ss += __shfl_xor(ss, 1); ss += __shfl_xor(ss, 2); ss += __shfl_xor(ss, 4); ss += __shfl_xor(ss, 8);
;         const float rstd = rsqrtf(ss * (1.f / 128.f) + 1e-6f);
; #pragma unroll
;         for (int e = 0; e < 8; ++e) o[e] = o[e] * rstd * (e < 4 ? nw0[e & 3] : nw1[e & 3]) * siluf(gt[e]);
;         *(u32x4*)(Y + (size_t)(row0 + k) * DM + 512 * mx + chn) = pack8(o);
;     }
; }
	v_mul_f32_e32 v0, v0, v96
	v_mul_f32_e32 v118, v118, v120
	v_mul_f32_e32 v119, v119, v121
	v_mul_f32_e32 v4, v4, v97
	v_mul_f32_e32 v0, v0, v118
	v_mul_f32_e32 v4, v4, v119
	v_cvt_pk_bf16_f32 v154, v0, v4
	v_lshlrev_b32_e32 v118, 16, v9
	v_and_b32_e32 v119, 0xffff0000, v9
	v_mul_f32_e32 v120, v125, v118
	v_mul_f32_e32 v121, v125, v119
	v_exp_f32_e32 v120, v120
	v_exp_f32_e32 v121, v121
	v_mul_f32_e32 v1, v1, v150
	v_add_f32_e32 v120, 1.0, v120
	v_add_f32_e32 v121, 1.0, v121
	v_rcp_f32_e32 v120, v120
	v_rcp_f32_e32 v121, v121
	v_mul_f32_e32 v5, v5, v150
	v_mul_f32_e32 v1, v1, v98
	v_mul_f32_e32 v118, v118, v120
	v_mul_f32_e32 v119, v119, v121
	v_mul_f32_e32 v5, v5, v99
	v_mul_f32_e32 v1, v1, v118
	v_mul_f32_e32 v5, v5, v119
	v_cvt_pk_bf16_f32 v155, v1, v5
	v_lshlrev_b32_e32 v118, 16, v10
	v_and_b32_e32 v119, 0xffff0000, v10
	v_mul_f32_e32 v120, v125, v118
	v_mul_f32_e32 v121, v125, v119
	v_exp_f32_e32 v120, v120
	v_exp_f32_e32 v121, v121
	v_mul_f32_e32 v2, v2, v150
	v_add_f32_e32 v120, 1.0, v120
	v_add_f32_e32 v121, 1.0, v121
	v_rcp_f32_e32 v120, v120
	v_rcp_f32_e32 v121, v121
	v_mul_f32_e32 v6, v6, v150
	v_mul_f32_e32 v2, v2, v100
	v_mul_f32_e32 v118, v118, v120
	v_mul_f32_e32 v119, v119, v121
	v_mul_f32_e32 v6, v6, v101
	v_mul_f32_e32 v2, v2, v118
	v_mul_f32_e32 v6, v6, v119
	v_cvt_pk_bf16_f32 v156, v2, v6
	v_lshlrev_b32_e32 v118, 16, v11
	v_and_b32_e32 v119, 0xffff0000, v11
	v_mul_f32_e32 v120, v125, v118
	v_mul_f32_e32 v121, v125, v119
	v_exp_f32_e32 v120, v120
	v_exp_f32_e32 v121, v121
	v_mul_f32_e32 v3, v3, v150
	v_add_f32_e32 v120, 1.0, v120
	v_add_f32_e32 v121, 1.0, v121
	v_rcp_f32_e32 v120, v120
	v_rcp_f32_e32 v121, v121
	v_mul_f32_e32 v7, v7, v150
	v_mul_f32_e32 v3, v3, v102
	v_mul_f32_e32 v118, v118, v120
	v_mul_f32_e32 v119, v119, v121
	v_mul_f32_e32 v7, v7, v103
	v_mul_f32_e32 v3, v3, v118
	v_mul_f32_e32 v7, v7, v119
	v_cvt_pk_bf16_f32 v157, v3, v7
	global_store_dwordx4 v107, v[154:157], s[42:43] sc1
	s_add_u32 s24, s24, s6
	s_lshl_b32 s0, s7, 12
	s_add_u32 s36, s4, s0
	s_addc_u32 s37, s5, 0
	s_mul_i32 s0, s7, 0xe000
	s_add_u32 s38, s4, s0
	s_addc_u32 s39, s5, 0
	global_load_dwordx4 v[0:3], v104, s[36:37] nt
	global_load_dwordx4 v[4:7], v105, s[36:37] nt
	global_load_dwordx4 v[8:11], v106, s[38:39] nt
	s_add_u32 s7, s7, s6
	s_waitcnt vmcnt(10)
	v_and_b32_e32 v118, 0xffff0000, v12
	v_and_b32_e32 v119, 0xffff0000, v16
	v_lshlrev_b32_e32 v12, 16, v12
	v_lshlrev_b32_e32 v120, 16, v16
	v_add_f32_e32 v12, v12, v120
	v_add_f32_e32 v16, v118, v119
	v_mul_f32_e32 v142, v12, v12
	v_fmac_f32_e32 v142, v16, v16
	v_and_b32_e32 v118, 0xffff0000, v13
	v_and_b32_e32 v119, 0xffff0000, v17
	v_lshlrev_b32_e32 v13, 16, v13
	v_lshlrev_b32_e32 v120, 16, v17
	v_add_f32_e32 v13, v13, v120
	v_add_f32_e32 v17, v118, v119
	v_fmac_f32_e32 v142, v13, v13
	v_fmac_f32_e32 v142, v17, v17
	v_and_b32_e32 v118, 0xffff0000, v14
	v_and_b32_e32 v119, 0xffff0000, v18
	v_lshlrev_b32_e32 v14, 16, v14
	v_lshlrev_b32_e32 v120, 16, v18
	v_add_f32_e32 v14, v14, v120
	v_add_f32_e32 v18, v118, v119
	v_fmac_f32_e32 v142, v14, v14
	v_fmac_f32_e32 v142, v18, v18
	v_and_b32_e32 v118, 0xffff0000, v15
	v_and_b32_e32 v119, 0xffff0000, v19
	v_lshlrev_b32_e32 v15, 16, v15
	v_lshlrev_b32_e32 v120, 16, v19
	v_add_f32_e32 v15, v15, v120
	v_add_f32_e32 v19, v118, v119
	v_fmac_f32_e32 v142, v15, v15
	v_fmac_f32_e32 v142, v19, v19
	s_nop 1
	v_add_f32_dpp v142, v142, v142 quad_perm:[1,0,3,2] row_mask:0xf bank_mask:0xf
	s_nop 1
	v_add_f32_dpp v142, v142, v142 quad_perm:[2,3,0,1] row_mask:0xf bank_mask:0xf
	s_nop 1
	v_add_f32_dpp v142, v142, v142 row_half_mirror row_mask:0xf bank_mask:0xf
	s_nop 1
	v_add_f32_dpp v142, v142, v142 row_mirror row_mask:0xf bank_mask:0xf
	v_fmamk_f32 v142, v142, 0x3c000000, v124
	v_rsq_f32_e32 v150, v142
	s_lshl_b32 s0, s24, 14
	s_add_u32 s42, s4, s0
	s_addc_u32 s43, s5, 0
	v_lshlrev_b32_e32 v118, 16, v20
	v_and_b32_e32 v119, 0xffff0000, v20
	v_mul_f32_e32 v120, v125, v118
	v_mul_f32_e32 v121, v125, v119
	v_exp_f32_e32 v120, v120
	v_exp_f32_e32 v121, v121
	v_mul_f32_e32 v12, v12, v150
	v_add_f32_e32 v120, 1.0, v120
	v_add_f32_e32 v121, 1.0, v121
	v_rcp_f32_e32 v120, v120
	v_rcp_f32_e32 v121, v121
	v_mul_f32_e32 v16, v16, v150
	v_mul_f32_e32 v12, v12, v96
	v_mul_f32_e32 v118, v118, v120
	v_mul_f32_e32 v119, v119, v121
	v_mul_f32_e32 v16, v16, v97
	v_mul_f32_e32 v12, v12, v118
	v_mul_f32_e32 v16, v16, v119
	v_cvt_pk_bf16_f32 v158, v12, v16
	v_lshlrev_b32_e32 v118, 16, v21
	v_and_b32_e32 v119, 0xffff0000, v21
	v_mul_f32_e32 v120, v125, v118
	v_mul_f32_e32 v121, v125, v119
	v_exp_f32_e32 v120, v120
	v_exp_f32_e32 v121, v121
	v_mul_f32_e32 v13, v13, v150
	v_add_f32_e32 v120, 1.0, v120
	v_add_f32_e32 v121, 1.0, v121
	v_rcp_f32_e32 v120, v120
	v_rcp_f32_e32 v121, v121
	v_mul_f32_e32 v17, v17, v150
	v_mul_f32_e32 v13, v13, v98
	v_mul_f32_e32 v118, v118, v120
	v_mul_f32_e32 v119, v119, v121
	v_mul_f32_e32 v17, v17, v99
	v_mul_f32_e32 v13, v13, v118
	v_mul_f32_e32 v17, v17, v119
	v_cvt_pk_bf16_f32 v159, v13, v17
	v_lshlrev_b32_e32 v118, 16, v22
	v_and_b32_e32 v119, 0xffff0000, v22
	v_mul_f32_e32 v120, v125, v118
	v_mul_f32_e32 v121, v125, v119
	v_exp_f32_e32 v120, v120
	v_exp_f32_e32 v121, v121
	v_mul_f32_e32 v14, v14, v150
	v_add_f32_e32 v120, 1.0, v120
	v_add_f32_e32 v121, 1.0, v121
	v_rcp_f32_e32 v120, v120
	v_rcp_f32_e32 v121, v121
	v_mul_f32_e32 v18, v18, v150
	v_mul_f32_e32 v14, v14, v100
	v_mul_f32_e32 v118, v118, v120
	v_mul_f32_e32 v119, v119, v121
	v_mul_f32_e32 v18, v18, v101
	v_mul_f32_e32 v14, v14, v118
	v_mul_f32_e32 v18, v18, v119
	v_cvt_pk_bf16_f32 v160, v14, v18
	v_lshlrev_b32_e32 v118, 16, v23
	v_and_b32_e32 v119, 0xffff0000, v23
	v_mul_f32_e32 v120, v125, v118
	v_mul_f32_e32 v121, v125, v119
	v_exp_f32_e32 v120, v120
	v_exp_f32_e32 v121, v121
	v_mul_f32_e32 v15, v15, v150
	v_add_f32_e32 v120, 1.0, v120
	v_add_f32_e32 v121, 1.0, v121
	v_rcp_f32_e32 v120, v120
	v_rcp_f32_e32 v121, v121
	v_mul_f32_e32 v19, v19, v150
	v_mul_f32_e32 v15, v15, v102
	v_mul_f32_e32 v118, v118, v120
	v_mul_f32_e32 v119, v119, v121
	v_mul_f32_e32 v19, v19, v103
	v_mul_f32_e32 v15, v15, v118
	v_mul_f32_e32 v19, v19, v119
	v_cvt_pk_bf16_f32 v161, v15, v19
	global_store_dwordx4 v107, v[158:161], s[42:43] sc1
	s_add_u32 s24, s24, s6
	s_lshl_b32 s0, s7, 12
	s_add_u32 s36, s4, s0
	s_addc_u32 s37, s5, 0
	s_mul_i32 s0, s7, 0xe000
	s_add_u32 s38, s4, s0
	s_addc_u32 s39, s5, 0
	global_load_dwordx4 v[12:15], v104, s[36:37] nt
	global_load_dwordx4 v[16:19], v105, s[36:37] nt
	global_load_dwordx4 v[20:23], v106, s[38:39] nt
	s_add_u32 s7, s7, s6
	s_waitcnt vmcnt(11)
; DI void unpack8(u32x4 v, float* o) { o[0] = lo16(v.x); o[1] = hi16(v.x); o[2] = lo16(v.y); o[3] = hi16(v.y); o[4] = lo16(v.z); o[5] = hi16(v.z); o[6] = lo16(v.w); o[7] = hi16(v.w); }
; DI u32x4 pack8(const float* o) { u32x4 r; r.x = pk2(o[0], o[1]); r.y = pk2(o[2], o[3]); r.z = pk2(o[4], o[5]); r.w = pk2(o[6], o[7]); return r; }
; DI float siluf(float x) { return x * __builtin_amdgcn_rcpf(1.f + __expf(-x)); }
; DI void finish_item(const P& p, int l, int r16) {
;     ...
;     for (int k = 0; k < 4; ++k) {
;         float a[8], b[8], o[8], gt[8];
;         unpack8(ra[k], a); unpack8(rb[k], b); unpack8(rg[k], gt);
;         float ss = 0.f;
; #pragma unroll
;         for (int e = 0; e < 8; ++e) { o[e] = a[e] + b[e]; ss += o[e] * o[e]; }
;         ss += __shfl_xor(ss, 1); ss += __shfl_xor(ss, 2); ss += __shfl_xor(ss, 4); ss += __shfl_xor(ss, 8);
;         const float rstd = rsqrtf(ss * (1.f / 128.f) + 1e-6f);
; #pragma unroll
;         for (int e = 0; e < 8; ++e) o[e] = o[e] * rstd * (e < 4 ? nw0[e & 3] : nw1[e & 3]) * siluf(gt[e]);
;         *(u32x4*)(Y + (size_t)(row0 + k) * DM + 512 * mx + chn) = pack8(o);
;     }
; }
	v_and_b32_e32 v118, 0xffff0000, v24
	v_and_b32_e32 v119, 0xffff0000, v28
	v_lshlrev_b32_e32 v24, 16, v24
	v_lshlrev_b32_e32 v120, 16, v28
	v_add_f32_e32 v24, v24, v120
	v_add_f32_e32 v28, v118, v119
	v_mul_f32_e32 v142, v24, v24
	v_fmac_f32_e32 v142, v28, v28
	v_and_b32_e32 v118, 0xffff0000, v25
	v_and_b32_e32 v119, 0xffff0000, v29
	v_lshlrev_b32_e32 v25, 16, v25
	v_lshlrev_b32_e32 v120, 16, v29
	v_add_f32_e32 v25, v25, v120
	v_add_f32_e32 v29, v118, v119
	v_fmac_f32_e32 v142, v25, v25
	v_fmac_f32_e32 v142, v29, v29
	v_and_b32_e32 v118, 0xffff0000, v26
	v_and_b32_e32 v119, 0xffff0000, v30
	v_lshlrev_b32_e32 v26, 16, v26
	v_lshlrev_b32_e32 v120, 16, v30
	v_add_f32_e32 v26, v26, v120
	v_add_f32_e32 v30, v118, v119
	v_fmac_f32_e32 v142, v26, v26
	v_fmac_f32_e32 v142, v30, v30
	v_and_b32_e32 v118, 0xffff0000, v27
	v_and_b32_e32 v119, 0xffff0000, v31
	v_lshlrev_b32_e32 v27, 16, v27
	v_lshlrev_b32_e32 v120, 16, v31
	v_add_f32_e32 v27, v27, v120
	v_add_f32_e32 v31, v118, v119
	v_fmac_f32_e32 v142, v27, v27
	v_fmac_f32_e32 v142, v31, v31
	s_nop 1
	v_add_f32_dpp v142, v142, v142 quad_perm:[1,0,3,2] row_mask:0xf bank_mask:0xf
	s_nop 1
	v_add_f32_dpp v142, v142, v142 quad_perm:[2,3,0,1] row_mask:0xf bank_mask:0xf
	s_nop 1
	v_add_f32_dpp v142, v142, v142 row_half_mirror row_mask:0xf bank_mask:0xf
	s_nop 1
	v_add_f32_dpp v142, v142, v142 row_mirror row_mask:0xf bank_mask:0xf
	v_fmamk_f32 v142, v142, 0x3c000000, v124
	v_rsq_f32_e32 v150, v142
	s_lshl_b32 s0, s24, 14
	s_add_u32 s42, s4, s0
	s_addc_u32 s43, s5, 0
	v_lshlrev_b32_e32 v118, 16, v32
	v_and_b32_e32 v119, 0xffff0000, v32
	v_mul_f32_e32 v120, v125, v118
	v_mul_f32_e32 v121, v125, v119
	v_exp_f32_e32 v120, v120
	v_exp_f32_e32 v121, v121
	v_mul_f32_e32 v24, v24, v150
	v_add_f32_e32 v120, 1.0, v120
	v_add_f32_e32 v121, 1.0, v121
	v_rcp_f32_e32 v120, v120
	v_rcp_f32_e32 v121, v121
	v_mul_f32_e32 v28, v28, v150
	v_mul_f32_e32 v24, v24, v96
	v_mul_f32_e32 v118, v118, v120
	v_mul_f32_e32 v119, v119, v121
	v_mul_f32_e32 v28, v28, v97
	v_mul_f32_e32 v24, v24, v118
	v_mul_f32_e32 v28, v28, v119
	v_cvt_pk_bf16_f32 v154, v24, v28
	v_lshlrev_b32_e32 v118, 16, v33
	v_and_b32_e32 v119, 0xffff0000, v33
	v_mul_f32_e32 v120, v125, v118
	v_mul_f32_e32 v121, v125, v119
	v_exp_f32_e32 v120, v120
	v_exp_f32_e32 v121, v121
	v_mul_f32_e32 v25, v25, v150
	v_add_f32_e32 v120, 1.0, v120
	v_add_f32_e32 v121, 1.0, v121
	v_rcp_f32_e32 v120, v120
	v_rcp_f32_e32 v121, v121
	v_mul_f32_e32 v29, v29, v150
	v_mul_f32_e32 v25, v25, v98
	v_mul_f32_e32 v118, v118, v120
	v_mul_f32_e32 v119, v119, v121
	v_mul_f32_e32 v29, v29, v99
	v_mul_f32_e32 v25, v25, v118
	v_mul_f32_e32 v29, v29, v119
	v_cvt_pk_bf16_f32 v155, v25, v29
	v_lshlrev_b32_e32 v118, 16, v34
	v_and_b32_e32 v119, 0xffff0000, v34
	v_mul_f32_e32 v120, v125, v118
	v_mul_f32_e32 v121, v125, v119
	v_exp_f32_e32 v120, v120
	v_exp_f32_e32 v121, v121
	v_mul_f32_e32 v26, v26, v150
	v_add_f32_e32 v120, 1.0, v120
	v_add_f32_e32 v121, 1.0, v121
	v_rcp_f32_e32 v120, v120
	v_rcp_f32_e32 v121, v121
	v_mul_f32_e32 v30, v30, v150
	v_mul_f32_e32 v26, v26, v100
	v_mul_f32_e32 v118, v118, v120
	v_mul_f32_e32 v119, v119, v121
	v_mul_f32_e32 v30, v30, v101
	v_mul_f32_e32 v26, v26, v118
	v_mul_f32_e32 v30, v30, v119
	v_cvt_pk_bf16_f32 v156, v26, v30
	v_lshlrev_b32_e32 v118, 16, v35
	v_and_b32_e32 v119, 0xffff0000, v35
	v_mul_f32_e32 v120, v125, v118
	v_mul_f32_e32 v121, v125, v119
	v_exp_f32_e32 v120, v120
	v_exp_f32_e32 v121, v121
	v_mul_f32_e32 v27, v27, v150
	v_add_f32_e32 v120, 1.0, v120
	v_add_f32_e32 v121, 1.0, v121
	v_rcp_f32_e32 v120, v120
	v_rcp_f32_e32 v121, v121
	v_mul_f32_e32 v31, v31, v150
	v_mul_f32_e32 v27, v27, v102
	v_mul_f32_e32 v118, v118, v120
	v_mul_f32_e32 v119, v119, v121
	v_mul_f32_e32 v31, v31, v103
	v_mul_f32_e32 v27, v27, v118
	v_mul_f32_e32 v31, v31, v119
	v_cvt_pk_bf16_f32 v157, v27, v31
	global_store_dwordx4 v107, v[154:157], s[42:43] sc1
	s_add_u32 s24, s24, s6
	s_lshl_b32 s0, s7, 12
	s_add_u32 s36, s4, s0
	s_addc_u32 s37, s5, 0
	s_mul_i32 s0, s7, 0xe000
	s_add_u32 s38, s4, s0
	s_addc_u32 s39, s5, 0
	global_load_dwordx4 v[24:27], v104, s[36:37] nt
	global_load_dwordx4 v[28:31], v105, s[36:37] nt
	global_load_dwordx4 v[32:35], v106, s[38:39] nt
	s_add_u32 s7, s7, s6
	s_waitcnt vmcnt(12)
; DI void unpack8(u32x4 v, float* o) { o[0] = lo16(v.x); o[1] = hi16(v.x); o[2] = lo16(v.y); o[3] = hi16(v.y); o[4] = lo16(v.z); o[5] = hi16(v.z); o[6] = lo16(v.w); o[7] = hi16(v.w); }
; DI u32x4 pack8(const float* o) { u32x4 r; r.x = pk2(o[0], o[1]); r.y = pk2(o[2], o[3]); r.z = pk2(o[4], o[5]); r.w = pk2(o[6], o[7]); return r; }
; DI float siluf(float x) { return x * __builtin_amdgcn_rcpf(1.f + __expf(-x)); }
; DI void finish_item(const P& p, int l, int r16) {
;     ...
;     for (int k = 0; k < 4; ++k) {
;         float a[8], b[8], o[8], gt[8];
;         unpack8(ra[k], a); unpack8(rb[k], b); unpack8(rg[k], gt);
;         float ss = 0.f;
; #pragma unroll
;         for (int e = 0; e < 8; ++e) { o[e] = a[e] + b[e]; ss += o[e] * o[e]; }
;         ss += __shfl_xor(ss, 1); ss += __shfl_xor(ss, 2); ss += __shfl_xor(ss, 4); ss += __shfl_xor(ss, 8);
;         const float rstd = rsqrtf(ss * (1.f / 128.f) + 1e-6f);
; #pragma unroll
;         for (int e = 0; e < 8; ++e) o[e] = o[e] * rstd * (e < 4 ? nw0[e & 3] : nw1[e & 3]) * siluf(gt[e]);
;         *(u32x4*)(Y + (size_t)(row0 + k) * DM + 512 * mx + chn) = pack8(o);
;     }
; }
	v_and_b32_e32 v118, 0xffff0000, v36
	v_and_b32_e32 v119, 0xffff0000, v40
	v_lshlrev_b32_e32 v36, 16, v36
	v_lshlrev_b32_e32 v120, 16, v40
	v_add_f32_e32 v36, v36, v120
	v_add_f32_e32 v40, v118, v119
	v_mul_f32_e32 v142, v36, v36
	v_fmac_f32_e32 v142, v40, v40
	v_and_b32_e32 v118, 0xffff0000, v37
	v_and_b32_e32 v119, 0xffff0000, v41
	v_lshlrev_b32_e32 v37, 16, v37
	v_lshlrev_b32_e32 v120, 16, v41
	v_add_f32_e32 v37, v37, v120
	v_add_f32_e32 v41, v118, v119
	v_fmac_f32_e32 v142, v37, v37
	v_fmac_f32_e32 v142, v41, v41
	v_and_b32_e32 v118, 0xffff0000, v38
	v_and_b32_e32 v119, 0xffff0000, v42
	v_lshlrev_b32_e32 v38, 16, v38
	v_lshlrev_b32_e32 v120, 16, v42
	v_add_f32_e32 v38, v38, v120
	v_add_f32_e32 v42, v118, v119
	v_fmac_f32_e32 v142, v38, v38
	v_fmac_f32_e32 v142, v42, v42
	v_and_b32_e32 v118, 0xffff0000, v39
	v_and_b32_e32 v119, 0xffff0000, v43
	v_lshlrev_b32_e32 v39, 16, v39
	v_lshlrev_b32_e32 v120, 16, v43
	v_add_f32_e32 v39, v39, v120
	v_add_f32_e32 v43, v118, v119
	v_fmac_f32_e32 v142, v39, v39
	v_fmac_f32_e32 v142, v43, v43
	s_nop 1
	v_add_f32_dpp v142, v142, v142 quad_perm:[1,0,3,2] row_mask:0xf bank_mask:0xf
	s_nop 1
	v_add_f32_dpp v142, v142, v142 quad_perm:[2,3,0,1] row_mask:0xf bank_mask:0xf
	s_nop 1
	v_add_f32_dpp v142, v142, v142 row_half_mirror row_mask:0xf bank_mask:0xf
	s_nop 1
	v_add_f32_dpp v142, v142, v142 row_mirror row_mask:0xf bank_mask:0xf
	v_fmamk_f32 v142, v142, 0x3c000000, v124
	v_rsq_f32_e32 v150, v142
	s_lshl_b32 s0, s24, 14
	s_add_u32 s42, s4, s0
	s_addc_u32 s43, s5, 0
	v_lshlrev_b32_e32 v118, 16, v44
	v_and_b32_e32 v119, 0xffff0000, v44
	v_mul_f32_e32 v120, v125, v118
	v_mul_f32_e32 v121, v125, v119
	v_exp_f32_e32 v120, v120
	v_exp_f32_e32 v121, v121
	v_mul_f32_e32 v36, v36, v150
	v_add_f32_e32 v120, 1.0, v120
	v_add_f32_e32 v121, 1.0, v121
	v_rcp_f32_e32 v120, v120
	v_rcp_f32_e32 v121, v121
	v_mul_f32_e32 v40, v40, v150
	v_mul_f32_e32 v36, v36, v96
	v_mul_f32_e32 v118, v118, v120
	v_mul_f32_e32 v119, v119, v121
	v_mul_f32_e32 v40, v40, v97
	v_mul_f32_e32 v36, v36, v118
	v_mul_f32_e32 v40, v40, v119
	v_cvt_pk_bf16_f32 v158, v36, v40
	v_lshlrev_b32_e32 v118, 16, v45
	v_and_b32_e32 v119, 0xffff0000, v45
	v_mul_f32_e32 v120, v125, v118
	v_mul_f32_e32 v121, v125, v119
	v_exp_f32_e32 v120, v120
	v_exp_f32_e32 v121, v121
	v_mul_f32_e32 v37, v37, v150
	v_add_f32_e32 v120, 1.0, v120
	v_add_f32_e32 v121, 1.0, v121
	v_rcp_f32_e32 v120, v120
	v_rcp_f32_e32 v121, v121
	v_mul_f32_e32 v41, v41, v150
	v_mul_f32_e32 v37, v37, v98
	v_mul_f32_e32 v118, v118, v120
	v_mul_f32_e32 v119, v119, v121
	v_mul_f32_e32 v41, v41, v99
	v_mul_f32_e32 v37, v37, v118
	v_mul_f32_e32 v41, v41, v119
	v_cvt_pk_bf16_f32 v159, v37, v41
	v_lshlrev_b32_e32 v118, 16, v46
	v_and_b32_e32 v119, 0xffff0000, v46
	v_mul_f32_e32 v120, v125, v118
	v_mul_f32_e32 v121, v125, v119
	v_exp_f32_e32 v120, v120
	v_exp_f32_e32 v121, v121
	v_mul_f32_e32 v38, v38, v150
	v_add_f32_e32 v120, 1.0, v120
	v_add_f32_e32 v121, 1.0, v121
	v_rcp_f32_e32 v120, v120
	v_rcp_f32_e32 v121, v121
	v_mul_f32_e32 v42, v42, v150
	v_mul_f32_e32 v38, v38, v100
	v_mul_f32_e32 v118, v118, v120
	v_mul_f32_e32 v119, v119, v121
	v_mul_f32_e32 v42, v42, v101
	v_mul_f32_e32 v38, v38, v118
	v_mul_f32_e32 v42, v42, v119
	v_cvt_pk_bf16_f32 v160, v38, v42
	v_lshlrev_b32_e32 v118, 16, v47
	v_and_b32_e32 v119, 0xffff0000, v47
	v_mul_f32_e32 v120, v125, v118
	v_mul_f32_e32 v121, v125, v119
	v_exp_f32_e32 v120, v120
	v_exp_f32_e32 v121, v121
	v_mul_f32_e32 v39, v39, v150
	v_add_f32_e32 v120, 1.0, v120
	v_add_f32_e32 v121, 1.0, v121
	v_rcp_f32_e32 v120, v120
	v_rcp_f32_e32 v121, v121
	v_mul_f32_e32 v43, v43, v150
	v_mul_f32_e32 v39, v39, v102
	v_mul_f32_e32 v118, v118, v120
	v_mul_f32_e32 v119, v119, v121
	v_mul_f32_e32 v43, v43, v103
	v_mul_f32_e32 v39, v39, v118
	v_mul_f32_e32 v43, v43, v119
	v_cvt_pk_bf16_f32 v161, v39, v43
	global_store_dwordx4 v107, v[158:161], s[42:43] sc1
	s_add_u32 s24, s24, s6
	s_lshl_b32 s0, s7, 12
	s_add_u32 s36, s4, s0
	s_addc_u32 s37, s5, 0
	s_mul_i32 s0, s7, 0xe000
	s_add_u32 s38, s4, s0
	s_addc_u32 s39, s5, 0
	global_load_dwordx4 v[36:39], v104, s[36:37] nt
	global_load_dwordx4 v[40:43], v105, s[36:37] nt
	global_load_dwordx4 v[44:47], v106, s[38:39] nt
	s_add_u32 s7, s7, s6
	s_waitcnt vmcnt(12)
; DI void unpack8(u32x4 v, float* o) { o[0] = lo16(v.x); o[1] = hi16(v.x); o[2] = lo16(v.y); o[3] = hi16(v.y); o[4] = lo16(v.z); o[5] = hi16(v.z); o[6] = lo16(v.w); o[7] = hi16(v.w); }
; DI u32x4 pack8(const float* o) { u32x4 r; r.x = pk2(o[0], o[1]); r.y = pk2(o[2], o[3]); r.z = pk2(o[4], o[5]); r.w = pk2(o[6], o[7]); return r; }
; DI float siluf(float x) { return x * __builtin_amdgcn_rcpf(1.f + __expf(-x)); }
; DI void finish_item(const P& p, int l, int r16) {
;     ...
;     for (int k = 0; k < 4; ++k) {
;         float a[8], b[8], o[8], gt[8];
;         unpack8(ra[k], a); unpack8(rb[k], b); unpack8(rg[k], gt);
;         float ss = 0.f;
; #pragma unroll
;         for (int e = 0; e < 8; ++e) { o[e] = a[e] + b[e]; ss += o[e] * o[e]; }
;         ss += __shfl_xor(ss, 1); ss += __shfl_xor(ss, 2); ss += __shfl_xor(ss, 4); ss += __shfl_xor(ss, 8);
;         const float rstd = rsqrtf(ss * (1.f / 128.f) + 1e-6f);
; #pragma unroll
;         for (int e = 0; e < 8; ++e) o[e] = o[e] * rstd * (e < 4 ? nw0[e & 3] : nw1[e & 3]) * siluf(gt[e]);
;         *(u32x4*)(Y + (size_t)(row0 + k) * DM + 512 * mx + chn) = pack8(o);
;     }
; }
	v_and_b32_e32 v118, 0xffff0000, v0
	v_and_b32_e32 v119, 0xffff0000, v4
	v_lshlrev_b32_e32 v0, 16, v0
	v_lshlrev_b32_e32 v120, 16, v4
	v_add_f32_e32 v0, v0, v120
	v_add_f32_e32 v4, v118, v119
	v_mul_f32_e32 v142, v0, v0
	v_fmac_f32_e32 v142, v4, v4
	v_and_b32_e32 v118, 0xffff0000, v1
	v_and_b32_e32 v119, 0xffff0000, v5
	v_lshlrev_b32_e32 v1, 16, v1
	v_lshlrev_b32_e32 v120, 16, v5
	v_add_f32_e32 v1, v1, v120
	v_add_f32_e32 v5, v118, v119
	v_fmac_f32_e32 v142, v1, v1
	v_fmac_f32_e32 v142, v5, v5
	v_and_b32_e32 v118, 0xffff0000, v2
	v_and_b32_e32 v119, 0xffff0000, v6
	v_lshlrev_b32_e32 v2, 16, v2
	v_lshlrev_b32_e32 v120, 16, v6
	v_add_f32_e32 v2, v2, v120
	v_add_f32_e32 v6, v118, v119
	v_fmac_f32_e32 v142, v2, v2
	v_fmac_f32_e32 v142, v6, v6
	v_and_b32_e32 v118, 0xffff0000, v3
	v_and_b32_e32 v119, 0xffff0000, v7
	v_lshlrev_b32_e32 v3, 16, v3
	v_lshlrev_b32_e32 v120, 16, v7
	v_add_f32_e32 v3, v3, v120
	v_add_f32_e32 v7, v118, v119
	v_fmac_f32_e32 v142, v3, v3
	v_fmac_f32_e32 v142, v7, v7
	s_nop 1
	v_add_f32_dpp v142, v142, v142 quad_perm:[1,0,3,2] row_mask:0xf bank_mask:0xf
	s_nop 1
	v_add_f32_dpp v142, v142, v142 quad_perm:[2,3,0,1] row_mask:0xf bank_mask:0xf
	s_nop 1
	v_add_f32_dpp v142, v142, v142 row_half_mirror row_mask:0xf bank_mask:0xf
	s_nop 1
	v_add_f32_dpp v142, v142, v142 row_mirror row_mask:0xf bank_mask:0xf
	v_fmamk_f32 v142, v142, 0x3c000000, v124
	v_rsq_f32_e32 v150, v142
	s_lshl_b32 s0, s24, 14
	s_add_u32 s42, s4, s0
	s_addc_u32 s43, s5, 0
	v_lshlrev_b32_e32 v118, 16, v8
	v_and_b32_e32 v119, 0xffff0000, v8
	v_mul_f32_e32 v120, v125, v118
	v_mul_f32_e32 v121, v125, v119
	v_exp_f32_e32 v120, v120
	v_exp_f32_e32 v121, v121
	v_mul_f32_e32 v0, v0, v150
	v_add_f32_e32 v120, 1.0, v120
	v_add_f32_e32 v121, 1.0, v121
	v_rcp_f32_e32 v120, v120
	v_rcp_f32_e32 v121, v121
	v_mul_f32_e32 v4, v4, v150
	v_mul_f32_e32 v0, v0, v96
	v_mul_f32_e32 v118, v118, v120
	v_mul_f32_e32 v119, v119, v121
	v_mul_f32_e32 v4, v4, v97
	v_mul_f32_e32 v0, v0, v118
	v_mul_f32_e32 v4, v4, v119
	v_cvt_pk_bf16_f32 v154, v0, v4
	v_lshlrev_b32_e32 v118, 16, v9
	v_and_b32_e32 v119, 0xffff0000, v9
	v_mul_f32_e32 v120, v125, v118
	v_mul_f32_e32 v121, v125, v119
	v_exp_f32_e32 v120, v120
	v_exp_f32_e32 v121, v121
	v_mul_f32_e32 v1, v1, v150
	v_add_f32_e32 v120, 1.0, v120
	v_add_f32_e32 v121, 1.0, v121
	v_rcp_f32_e32 v120, v120
	v_rcp_f32_e32 v121, v121
	v_mul_f32_e32 v5, v5, v150
	v_mul_f32_e32 v1, v1, v98
	v_mul_f32_e32 v118, v118, v120
	v_mul_f32_e32 v119, v119, v121
	v_mul_f32_e32 v5, v5, v99
	v_mul_f32_e32 v1, v1, v118
	v_mul_f32_e32 v5, v5, v119
	v_cvt_pk_bf16_f32 v155, v1, v5
	v_lshlrev_b32_e32 v118, 16, v10
	v_and_b32_e32 v119, 0xffff0000, v10
	v_mul_f32_e32 v120, v125, v118
	v_mul_f32_e32 v121, v125, v119
	v_exp_f32_e32 v120, v120
	v_exp_f32_e32 v121, v121
	v_mul_f32_e32 v2, v2, v150
	v_add_f32_e32 v120, 1.0, v120
	v_add_f32_e32 v121, 1.0, v121
	v_rcp_f32_e32 v120, v120
	v_rcp_f32_e32 v121, v121
	v_mul_f32_e32 v6, v6, v150
	v_mul_f32_e32 v2, v2, v100
	v_mul_f32_e32 v118, v118, v120
	v_mul_f32_e32 v119, v119, v121
	v_mul_f32_e32 v6, v6, v101
	v_mul_f32_e32 v2, v2, v118
	v_mul_f32_e32 v6, v6, v119
	v_cvt_pk_bf16_f32 v156, v2, v6
	v_lshlrev_b32_e32 v118, 16, v11
	v_and_b32_e32 v119, 0xffff0000, v11
	v_mul_f32_e32 v120, v125, v118
	v_mul_f32_e32 v121, v125, v119
	v_exp_f32_e32 v120, v120
	v_exp_f32_e32 v121, v121
	v_mul_f32_e32 v3, v3, v150
	v_add_f32_e32 v120, 1.0, v120
	v_add_f32_e32 v121, 1.0, v121
	v_rcp_f32_e32 v120, v120
	v_rcp_f32_e32 v121, v121
	v_mul_f32_e32 v7, v7, v150
	v_mul_f32_e32 v3, v3, v102
	v_mul_f32_e32 v118, v118, v120
	v_mul_f32_e32 v119, v119, v121
	v_mul_f32_e32 v7, v7, v103
	v_mul_f32_e32 v3, v3, v118
	v_mul_f32_e32 v7, v7, v119
	v_cvt_pk_bf16_f32 v157, v3, v7
	global_store_dwordx4 v107, v[154:157], s[42:43] sc1
	s_add_u32 s24, s24, s6
	s_lshl_b32 s0, s7, 12
	s_add_u32 s36, s4, s0
	s_addc_u32 s37, s5, 0
	s_mul_i32 s0, s7, 0xe000
	s_add_u32 s38, s4, s0
	s_addc_u32 s39, s5, 0
	global_load_dwordx4 v[0:3], v104, s[36:37] nt
	global_load_dwordx4 v[4:7], v105, s[36:37] nt
	global_load_dwordx4 v[8:11], v106, s[38:39] nt
	s_add_u32 s7, s7, s6
	s_waitcnt vmcnt(12)
	v_and_b32_e32 v118, 0xffff0000, v12
	v_and_b32_e32 v119, 0xffff0000, v16
	v_lshlrev_b32_e32 v12, 16, v12
	v_lshlrev_b32_e32 v120, 16, v16
	v_add_f32_e32 v12, v12, v120
	v_add_f32_e32 v16, v118, v119
	v_mul_f32_e32 v142, v12, v12
	v_fmac_f32_e32 v142, v16, v16
	v_and_b32_e32 v118, 0xffff0000, v13
	v_and_b32_e32 v119, 0xffff0000, v17
	v_lshlrev_b32_e32 v13, 16, v13
	v_lshlrev_b32_e32 v120, 16, v17
	v_add_f32_e32 v13, v13, v120
	v_add_f32_e32 v17, v118, v119
	v_fmac_f32_e32 v142, v13, v13
	v_fmac_f32_e32 v142, v17, v17
	v_and_b32_e32 v118, 0xffff0000, v14
	v_and_b32_e32 v119, 0xffff0000, v18
	v_lshlrev_b32_e32 v14, 16, v14
	v_lshlrev_b32_e32 v120, 16, v18
	v_add_f32_e32 v14, v14, v120
	v_add_f32_e32 v18, v118, v119
	v_fmac_f32_e32 v142, v14, v14
	v_fmac_f32_e32 v142, v18, v18
	v_and_b32_e32 v118, 0xffff0000, v15
	v_and_b32_e32 v119, 0xffff0000, v19
	v_lshlrev_b32_e32 v15, 16, v15
	v_lshlrev_b32_e32 v120, 16, v19
	v_add_f32_e32 v15, v15, v120
	v_add_f32_e32 v19, v118, v119
	v_fmac_f32_e32 v142, v15, v15
	v_fmac_f32_e32 v142, v19, v19
	s_nop 1
	v_add_f32_dpp v142, v142, v142 quad_perm:[1,0,3,2] row_mask:0xf bank_mask:0xf
	s_nop 1
	v_add_f32_dpp v142, v142, v142 quad_perm:[2,3,0,1] row_mask:0xf bank_mask:0xf
	s_nop 1
	v_add_f32_dpp v142, v142, v142 row_half_mirror row_mask:0xf bank_mask:0xf
	s_nop 1
	v_add_f32_dpp v142, v142, v142 row_mirror row_mask:0xf bank_mask:0xf
	v_fmamk_f32 v142, v142, 0x3c000000, v124
	v_rsq_f32_e32 v150, v142
	s_lshl_b32 s0, s24, 14
	s_add_u32 s42, s4, s0
	s_addc_u32 s43, s5, 0
; DI void unpack8(u32x4 v, float* o) { o[0] = lo16(v.x); o[1] = hi16(v.x); o[2] = lo16(v.y); o[3] = hi16(v.y); o[4] = lo16(v.z); o[5] = hi16(v.z); o[6] = lo16(v.w); o[7] = hi16(v.w); }
; DI u32x4 pack8(const float* o) { u32x4 r; r.x = pk2(o[0], o[1]); r.y = pk2(o[2], o[3]); r.z = pk2(o[4], o[5]); r.w = pk2(o[6], o[7]); return r; }
; DI float siluf(float x) { return x * __builtin_amdgcn_rcpf(1.f + __expf(-x)); }
; DI void finish_item(const P& p, int l, int r16) {
;     ...
;     for (int k = 0; k < 4; ++k) {
;         float a[8], b[8], o[8], gt[8];
;         unpack8(ra[k], a); unpack8(rb[k], b); unpack8(rg[k], gt);
;         float ss = 0.f;
; #pragma unroll
;         for (int e = 0; e < 8; ++e) { o[e] = a[e] + b[e]; ss += o[e] * o[e]; }
;         ss += __shfl_xor(ss, 1); ss += __shfl_xor(ss, 2); ss += __shfl_xor(ss, 4); ss += __shfl_xor(ss, 8);
;         const float rstd = rsqrtf(ss * (1.f / 128.f) + 1e-6f);
; #pragma unroll
;         for (int e = 0; e < 8; ++e) o[e] = o[e] * rstd * (e < 4 ? nw0[e & 3] : nw1[e & 3]) * siluf(gt[e]);
;         *(u32x4*)(Y + (size_t)(row0 + k) * DM + 512 * mx + chn) = pack8(o);
;     }
; }
	v_lshlrev_b32_e32 v118, 16, v20
	v_and_b32_e32 v119, 0xffff0000, v20
	v_mul_f32_e32 v120, v125, v118
	v_mul_f32_e32 v121, v125, v119
	v_exp_f32_e32 v120, v120
	v_exp_f32_e32 v121, v121
	v_mul_f32_e32 v12, v12, v150
	v_add_f32_e32 v120, 1.0, v120
	v_add_f32_e32 v121, 1.0, v121
	v_rcp_f32_e32 v120, v120
	v_rcp_f32_e32 v121, v121
	v_mul_f32_e32 v16, v16, v150
	v_mul_f32_e32 v12, v12, v96
	v_mul_f32_e32 v118, v118, v120
	v_mul_f32_e32 v119, v119, v121
	v_mul_f32_e32 v16, v16, v97
	v_mul_f32_e32 v12, v12, v118
	v_mul_f32_e32 v16, v16, v119
	v_cvt_pk_bf16_f32 v158, v12, v16
	v_lshlrev_b32_e32 v118, 16, v21
	v_and_b32_e32 v119, 0xffff0000, v21
	v_mul_f32_e32 v120, v125, v118
	v_mul_f32_e32 v121, v125, v119
	v_exp_f32_e32 v120, v120
	v_exp_f32_e32 v121, v121
	v_mul_f32_e32 v13, v13, v150
	v_add_f32_e32 v120, 1.0, v120
	v_add_f32_e32 v121, 1.0, v121
	v_rcp_f32_e32 v120, v120
	v_rcp_f32_e32 v121, v121
	v_mul_f32_e32 v17, v17, v150
	v_mul_f32_e32 v13, v13, v98
	v_mul_f32_e32 v118, v118, v120
	v_mul_f32_e32 v119, v119, v121
	v_mul_f32_e32 v17, v17, v99
	v_mul_f32_e32 v13, v13, v118
	v_mul_f32_e32 v17, v17, v119
	v_cvt_pk_bf16_f32 v159, v13, v17
	v_lshlrev_b32_e32 v118, 16, v22
	v_and_b32_e32 v119, 0xffff0000, v22
	v_mul_f32_e32 v120, v125, v118
	v_mul_f32_e32 v121, v125, v119
	v_exp_f32_e32 v120, v120
	v_exp_f32_e32 v121, v121
	v_mul_f32_e32 v14, v14, v150
	v_add_f32_e32 v120, 1.0, v120
	v_add_f32_e32 v121, 1.0, v121
	v_rcp_f32_e32 v120, v120
	v_rcp_f32_e32 v121, v121
	v_mul_f32_e32 v18, v18, v150
	v_mul_f32_e32 v14, v14, v100
	v_mul_f32_e32 v118, v118, v120
	v_mul_f32_e32 v119, v119, v121
	v_mul_f32_e32 v18, v18, v101
	v_mul_f32_e32 v14, v14, v118
	v_mul_f32_e32 v18, v18, v119
	v_cvt_pk_bf16_f32 v160, v14, v18
	v_lshlrev_b32_e32 v118, 16, v23
	v_and_b32_e32 v119, 0xffff0000, v23
	v_mul_f32_e32 v120, v125, v118
	v_mul_f32_e32 v121, v125, v119
	v_exp_f32_e32 v120, v120
	v_exp_f32_e32 v121, v121
	v_mul_f32_e32 v15, v15, v150
	v_add_f32_e32 v120, 1.0, v120
	v_add_f32_e32 v121, 1.0, v121
	v_rcp_f32_e32 v120, v120
	v_rcp_f32_e32 v121, v121
	v_mul_f32_e32 v19, v19, v150
	v_mul_f32_e32 v15, v15, v102
	v_mul_f32_e32 v118, v118, v120
	v_mul_f32_e32 v119, v119, v121
	v_mul_f32_e32 v19, v19, v103
	v_mul_f32_e32 v15, v15, v118
	v_mul_f32_e32 v19, v19, v119
	v_cvt_pk_bf16_f32 v161, v15, v19
	global_store_dwordx4 v107, v[158:161], s[42:43] sc1
	s_add_u32 s24, s24, s6
	s_waitcnt vmcnt(9)
	v_and_b32_e32 v118, 0xffff0000, v24
	v_and_b32_e32 v119, 0xffff0000, v28
	v_lshlrev_b32_e32 v24, 16, v24
	v_lshlrev_b32_e32 v120, 16, v28
	v_add_f32_e32 v24, v24, v120
	v_add_f32_e32 v28, v118, v119
	v_mul_f32_e32 v142, v24, v24
	v_fmac_f32_e32 v142, v28, v28
	v_and_b32_e32 v118, 0xffff0000, v25
	v_and_b32_e32 v119, 0xffff0000, v29
	v_lshlrev_b32_e32 v25, 16, v25
	v_lshlrev_b32_e32 v120, 16, v29
	v_add_f32_e32 v25, v25, v120
	v_add_f32_e32 v29, v118, v119
	v_fmac_f32_e32 v142, v25, v25
	v_fmac_f32_e32 v142, v29, v29
	v_and_b32_e32 v118, 0xffff0000, v26
	v_and_b32_e32 v119, 0xffff0000, v30
	v_lshlrev_b32_e32 v26, 16, v26
	v_lshlrev_b32_e32 v120, 16, v30
	v_add_f32_e32 v26, v26, v120
	v_add_f32_e32 v30, v118, v119
	v_fmac_f32_e32 v142, v26, v26
	v_fmac_f32_e32 v142, v30, v30
	v_and_b32_e32 v118, 0xffff0000, v27
	v_and_b32_e32 v119, 0xffff0000, v31
	v_lshlrev_b32_e32 v27, 16, v27
	v_lshlrev_b32_e32 v120, 16, v31
	v_add_f32_e32 v27, v27, v120
	v_add_f32_e32 v31, v118, v119
	v_fmac_f32_e32 v142, v27, v27
	v_fmac_f32_e32 v142, v31, v31
	s_nop 1
	v_add_f32_dpp v142, v142, v142 quad_perm:[1,0,3,2] row_mask:0xf bank_mask:0xf
	s_nop 1
	v_add_f32_dpp v142, v142, v142 quad_perm:[2,3,0,1] row_mask:0xf bank_mask:0xf
	s_nop 1
	v_add_f32_dpp v142, v142, v142 row_half_mirror row_mask:0xf bank_mask:0xf
	s_nop 1
	v_add_f32_dpp v142, v142, v142 row_mirror row_mask:0xf bank_mask:0xf
	v_fmamk_f32 v142, v142, 0x3c000000, v124
	v_rsq_f32_e32 v150, v142
	s_lshl_b32 s0, s24, 14
	s_add_u32 s42, s4, s0
	s_addc_u32 s43, s5, 0
	v_lshlrev_b32_e32 v118, 16, v32
	v_and_b32_e32 v119, 0xffff0000, v32
	v_mul_f32_e32 v120, v125, v118
	v_mul_f32_e32 v121, v125, v119
	v_exp_f32_e32 v120, v120
	v_exp_f32_e32 v121, v121
	v_mul_f32_e32 v24, v24, v150
	v_add_f32_e32 v120, 1.0, v120
	v_add_f32_e32 v121, 1.0, v121
	v_rcp_f32_e32 v120, v120
	v_rcp_f32_e32 v121, v121
	v_mul_f32_e32 v28, v28, v150
	v_mul_f32_e32 v24, v24, v96
	v_mul_f32_e32 v118, v118, v120
	v_mul_f32_e32 v119, v119, v121
	v_mul_f32_e32 v28, v28, v97
	v_mul_f32_e32 v24, v24, v118
	v_mul_f32_e32 v28, v28, v119
	v_cvt_pk_bf16_f32 v154, v24, v28
	v_lshlrev_b32_e32 v118, 16, v33
	v_and_b32_e32 v119, 0xffff0000, v33
	v_mul_f32_e32 v120, v125, v118
	v_mul_f32_e32 v121, v125, v119
	v_exp_f32_e32 v120, v120
	v_exp_f32_e32 v121, v121
	v_mul_f32_e32 v25, v25, v150
	v_add_f32_e32 v120, 1.0, v120
	v_add_f32_e32 v121, 1.0, v121
	v_rcp_f32_e32 v120, v120
	v_rcp_f32_e32 v121, v121
	v_mul_f32_e32 v29, v29, v150
	v_mul_f32_e32 v25, v25, v98
	v_mul_f32_e32 v118, v118, v120
	v_mul_f32_e32 v119, v119, v121
	v_mul_f32_e32 v29, v29, v99
	v_mul_f32_e32 v25, v25, v118
	v_mul_f32_e32 v29, v29, v119
	v_cvt_pk_bf16_f32 v155, v25, v29
	v_lshlrev_b32_e32 v118, 16, v34
	v_and_b32_e32 v119, 0xffff0000, v34
	v_mul_f32_e32 v120, v125, v118
	v_mul_f32_e32 v121, v125, v119
	v_exp_f32_e32 v120, v120
	v_exp_f32_e32 v121, v121
	v_mul_f32_e32 v26, v26, v150
	v_add_f32_e32 v120, 1.0, v120
	v_add_f32_e32 v121, 1.0, v121
	v_rcp_f32_e32 v120, v120
	v_rcp_f32_e32 v121, v121
	v_mul_f32_e32 v30, v30, v150
	v_mul_f32_e32 v26, v26, v100
	v_mul_f32_e32 v118, v118, v120
	v_mul_f32_e32 v119, v119, v121
	v_mul_f32_e32 v30, v30, v101
	v_mul_f32_e32 v26, v26, v118
	v_mul_f32_e32 v30, v30, v119
	v_cvt_pk_bf16_f32 v156, v26, v30
	v_lshlrev_b32_e32 v118, 16, v35
	v_and_b32_e32 v119, 0xffff0000, v35
	v_mul_f32_e32 v120, v125, v118
	v_mul_f32_e32 v121, v125, v119
	v_exp_f32_e32 v120, v120
	v_exp_f32_e32 v121, v121
	v_mul_f32_e32 v27, v27, v150
	v_add_f32_e32 v120, 1.0, v120
	v_add_f32_e32 v121, 1.0, v121
	v_rcp_f32_e32 v120, v120
	v_rcp_f32_e32 v121, v121
	v_mul_f32_e32 v31, v31, v150
	v_mul_f32_e32 v27, v27, v102
	v_mul_f32_e32 v118, v118, v120
	v_mul_f32_e32 v119, v119, v121
	v_mul_f32_e32 v31, v31, v103
	v_mul_f32_e32 v27, v27, v118
	v_mul_f32_e32 v31, v31, v119
	v_cvt_pk_bf16_f32 v157, v27, v31
	global_store_dwordx4 v107, v[154:157], s[42:43] sc1
	s_add_u32 s24, s24, s6
	s_waitcnt vmcnt(6)
; DI void unpack8(u32x4 v, float* o) { o[0] = lo16(v.x); o[1] = hi16(v.x); o[2] = lo16(v.y); o[3] = hi16(v.y); o[4] = lo16(v.z); o[5] = hi16(v.z); o[6] = lo16(v.w); o[7] = hi16(v.w); }
; DI u32x4 pack8(const float* o) { u32x4 r; r.x = pk2(o[0], o[1]); r.y = pk2(o[2], o[3]); r.z = pk2(o[4], o[5]); r.w = pk2(o[6], o[7]); return r; }
; DI float siluf(float x) { return x * __builtin_amdgcn_rcpf(1.f + __expf(-x)); }
; DI void finish_item(const P& p, int l, int r16) {
;     ...
;     for (int k = 0; k < 4; ++k) {
;         float a[8], b[8], o[8], gt[8];
;         unpack8(ra[k], a); unpack8(rb[k], b); unpack8(rg[k], gt);
;         float ss = 0.f;
; #pragma unroll
;         for (int e = 0; e < 8; ++e) { o[e] = a[e] + b[e]; ss += o[e] * o[e]; }
;         ss += __shfl_xor(ss, 1); ss += __shfl_xor(ss, 2); ss += __shfl_xor(ss, 4); ss += __shfl_xor(ss, 8);
;         const float rstd = rsqrtf(ss * (1.f / 128.f) + 1e-6f);
; #pragma unroll
;         for (int e = 0; e < 8; ++e) o[e] = o[e] * rstd * (e < 4 ? nw0[e & 3] : nw1[e & 3]) * siluf(gt[e]);
;         *(u32x4*)(Y + (size_t)(row0 + k) * DM + 512 * mx + chn) = pack8(o);
;     }
; }
	v_and_b32_e32 v118, 0xffff0000, v36
	v_and_b32_e32 v119, 0xffff0000, v40
	v_lshlrev_b32_e32 v36, 16, v36
	v_lshlrev_b32_e32 v120, 16, v40
	v_add_f32_e32 v36, v36, v120
	v_add_f32_e32 v40, v118, v119
	v_mul_f32_e32 v142, v36, v36
	v_fmac_f32_e32 v142, v40, v40
	v_and_b32_e32 v118, 0xffff0000, v37
	v_and_b32_e32 v119, 0xffff0000, v41
	v_lshlrev_b32_e32 v37, 16, v37
	v_lshlrev_b32_e32 v120, 16, v41
	v_add_f32_e32 v37, v37, v120
	v_add_f32_e32 v41, v118, v119
	v_fmac_f32_e32 v142, v37, v37
	v_fmac_f32_e32 v142, v41, v41
	v_and_b32_e32 v118, 0xffff0000, v38
	v_and_b32_e32 v119, 0xffff0000, v42
	v_lshlrev_b32_e32 v38, 16, v38
	v_lshlrev_b32_e32 v120, 16, v42
	v_add_f32_e32 v38, v38, v120
	v_add_f32_e32 v42, v118, v119
	v_fmac_f32_e32 v142, v38, v38
	v_fmac_f32_e32 v142, v42, v42
	v_and_b32_e32 v118, 0xffff0000, v39
	v_and_b32_e32 v119, 0xffff0000, v43
	v_lshlrev_b32_e32 v39, 16, v39
	v_lshlrev_b32_e32 v120, 16, v43
	v_add_f32_e32 v39, v39, v120
	v_add_f32_e32 v43, v118, v119
	v_fmac_f32_e32 v142, v39, v39
	v_fmac_f32_e32 v142, v43, v43
	s_nop 1
	v_add_f32_dpp v142, v142, v142 quad_perm:[1,0,3,2] row_mask:0xf bank_mask:0xf
	s_nop 1
	v_add_f32_dpp v142, v142, v142 quad_perm:[2,3,0,1] row_mask:0xf bank_mask:0xf
	s_nop 1
	v_add_f32_dpp v142, v142, v142 row_half_mirror row_mask:0xf bank_mask:0xf
	s_nop 1
	v_add_f32_dpp v142, v142, v142 row_mirror row_mask:0xf bank_mask:0xf
	v_fmamk_f32 v142, v142, 0x3c000000, v124
	v_rsq_f32_e32 v150, v142
	s_lshl_b32 s0, s24, 14
	s_add_u32 s42, s4, s0
	s_addc_u32 s43, s5, 0
	v_lshlrev_b32_e32 v118, 16, v44
	v_and_b32_e32 v119, 0xffff0000, v44
	v_mul_f32_e32 v120, v125, v118
	v_mul_f32_e32 v121, v125, v119
	v_exp_f32_e32 v120, v120
	v_exp_f32_e32 v121, v121
	v_mul_f32_e32 v36, v36, v150
	v_add_f32_e32 v120, 1.0, v120
	v_add_f32_e32 v121, 1.0, v121
	v_rcp_f32_e32 v120, v120
	v_rcp_f32_e32 v121, v121
	v_mul_f32_e32 v40, v40, v150
	v_mul_f32_e32 v36, v36, v96
	v_mul_f32_e32 v118, v118, v120
	v_mul_f32_e32 v119, v119, v121
	v_mul_f32_e32 v40, v40, v97
	v_mul_f32_e32 v36, v36, v118
	v_mul_f32_e32 v40, v40, v119
	v_cvt_pk_bf16_f32 v158, v36, v40
	v_lshlrev_b32_e32 v118, 16, v45
	v_and_b32_e32 v119, 0xffff0000, v45
	v_mul_f32_e32 v120, v125, v118
	v_mul_f32_e32 v121, v125, v119
	v_exp_f32_e32 v120, v120
	v_exp_f32_e32 v121, v121
	v_mul_f32_e32 v37, v37, v150
	v_add_f32_e32 v120, 1.0, v120
	v_add_f32_e32 v121, 1.0, v121
	v_rcp_f32_e32 v120, v120
	v_rcp_f32_e32 v121, v121
	v_mul_f32_e32 v41, v41, v150
	v_mul_f32_e32 v37, v37, v98
	v_mul_f32_e32 v118, v118, v120
	v_mul_f32_e32 v119, v119, v121
	v_mul_f32_e32 v41, v41, v99
	v_mul_f32_e32 v37, v37, v118
	v_mul_f32_e32 v41, v41, v119
	v_cvt_pk_bf16_f32 v159, v37, v41
	v_lshlrev_b32_e32 v118, 16, v46
	v_and_b32_e32 v119, 0xffff0000, v46
	v_mul_f32_e32 v120, v125, v118
	v_mul_f32_e32 v121, v125, v119
	v_exp_f32_e32 v120, v120
	v_exp_f32_e32 v121, v121
	v_mul_f32_e32 v38, v38, v150
	v_add_f32_e32 v120, 1.0, v120
	v_add_f32_e32 v121, 1.0, v121
	v_rcp_f32_e32 v120, v120
	v_rcp_f32_e32 v121, v121
	v_mul_f32_e32 v42, v42, v150
	v_mul_f32_e32 v38, v38, v100
	v_mul_f32_e32 v118, v118, v120
	v_mul_f32_e32 v119, v119, v121
	v_mul_f32_e32 v42, v42, v101
	v_mul_f32_e32 v38, v38, v118
	v_mul_f32_e32 v42, v42, v119
	v_cvt_pk_bf16_f32 v160, v38, v42
	v_lshlrev_b32_e32 v118, 16, v47
	v_and_b32_e32 v119, 0xffff0000, v47
	v_mul_f32_e32 v120, v125, v118
	v_mul_f32_e32 v121, v125, v119
	v_exp_f32_e32 v120, v120
	v_exp_f32_e32 v121, v121
	v_mul_f32_e32 v39, v39, v150
	v_add_f32_e32 v120, 1.0, v120
	v_add_f32_e32 v121, 1.0, v121
	v_rcp_f32_e32 v120, v120
	v_rcp_f32_e32 v121, v121
	v_mul_f32_e32 v43, v43, v150
	v_mul_f32_e32 v39, v39, v102
	v_mul_f32_e32 v118, v118, v120
	v_mul_f32_e32 v119, v119, v121
	v_mul_f32_e32 v43, v43, v103
	v_mul_f32_e32 v39, v39, v118
	v_mul_f32_e32 v43, v43, v119
	v_cvt_pk_bf16_f32 v161, v39, v43
	global_store_dwordx4 v107, v[158:161], s[42:43] sc1
	s_add_u32 s24, s24, s6
	s_waitcnt vmcnt(3)
; DI void unpack8(u32x4 v, float* o) { o[0] = lo16(v.x); o[1] = hi16(v.x); o[2] = lo16(v.y); o[3] = hi16(v.y); o[4] = lo16(v.z); o[5] = hi16(v.z); o[6] = lo16(v.w); o[7] = hi16(v.w); }
; DI u32x4 pack8(const float* o) { u32x4 r; r.x = pk2(o[0], o[1]); r.y = pk2(o[2], o[3]); r.z = pk2(o[4], o[5]); r.w = pk2(o[6], o[7]); return r; }
; DI float siluf(float x) { return x * __builtin_amdgcn_rcpf(1.f + __expf(-x)); }
; DI void finish_item(const P& p, int l, int r16) {
;     ...
;     for (int k = 0; k < 4; ++k) {
;         float a[8], b[8], o[8], gt[8];
;         unpack8(ra[k], a); unpack8(rb[k], b); unpack8(rg[k], gt);
;         float ss = 0.f;
; #pragma unroll
;         for (int e = 0; e < 8; ++e) { o[e] = a[e] + b[e]; ss += o[e] * o[e]; }
;         ss += __shfl_xor(ss, 1); ss += __shfl_xor(ss, 2); ss += __shfl_xor(ss, 4); ss += __shfl_xor(ss, 8);
;         const float rstd = rsqrtf(ss * (1.f / 128.f) + 1e-6f);
; #pragma unroll
;         for (int e = 0; e < 8; ++e) o[e] = o[e] * rstd * (e < 4 ? nw0[e & 3] : nw1[e & 3]) * siluf(gt[e]);
;         *(u32x4*)(Y + (size_t)(row0 + k) * DM + 512 * mx + chn) = pack8(o);
;     }
; }
	v_and_b32_e32 v118, 0xffff0000, v0
	v_and_b32_e32 v119, 0xffff0000, v4
	v_lshlrev_b32_e32 v0, 16, v0
	v_lshlrev_b32_e32 v120, 16, v4
	v_add_f32_e32 v0, v0, v120
	v_add_f32_e32 v4, v118, v119
	v_mul_f32_e32 v142, v0, v0
	v_fmac_f32_e32 v142, v4, v4
	v_and_b32_e32 v118, 0xffff0000, v1
	v_and_b32_e32 v119, 0xffff0000, v5
	v_lshlrev_b32_e32 v1, 16, v1
	v_lshlrev_b32_e32 v120, 16, v5
	v_add_f32_e32 v1, v1, v120
	v_add_f32_e32 v5, v118, v119
	v_fmac_f32_e32 v142, v1, v1
	v_fmac_f32_e32 v142, v5, v5
	v_and_b32_e32 v118, 0xffff0000, v2
	v_and_b32_e32 v119, 0xffff0000, v6
	v_lshlrev_b32_e32 v2, 16, v2
	v_lshlrev_b32_e32 v120, 16, v6
	v_add_f32_e32 v2, v2, v120
	v_add_f32_e32 v6, v118, v119
	v_fmac_f32_e32 v142, v2, v2
	v_fmac_f32_e32 v142, v6, v6
	v_and_b32_e32 v118, 0xffff0000, v3
	v_and_b32_e32 v119, 0xffff0000, v7
	v_lshlrev_b32_e32 v3, 16, v3
	v_lshlrev_b32_e32 v120, 16, v7
	v_add_f32_e32 v3, v3, v120
	v_add_f32_e32 v7, v118, v119
	v_fmac_f32_e32 v142, v3, v3
	v_fmac_f32_e32 v142, v7, v7
	s_nop 1
	v_add_f32_dpp v142, v142, v142 quad_perm:[1,0,3,2] row_mask:0xf bank_mask:0xf
	s_nop 1
	v_add_f32_dpp v142, v142, v142 quad_perm:[2,3,0,1] row_mask:0xf bank_mask:0xf
	s_nop 1
	v_add_f32_dpp v142, v142, v142 row_half_mirror row_mask:0xf bank_mask:0xf
	s_nop 1
	v_add_f32_dpp v142, v142, v142 row_mirror row_mask:0xf bank_mask:0xf
	v_fmamk_f32 v142, v142, 0x3c000000, v124
	v_rsq_f32_e32 v150, v142
	s_lshl_b32 s0, s24, 14
	s_add_u32 s42, s4, s0
	s_addc_u32 s43, s5, 0
	v_lshlrev_b32_e32 v118, 16, v8
	v_and_b32_e32 v119, 0xffff0000, v8
	v_mul_f32_e32 v120, v125, v118
	v_mul_f32_e32 v121, v125, v119
	v_exp_f32_e32 v120, v120
	v_exp_f32_e32 v121, v121
	v_mul_f32_e32 v0, v0, v150
	v_add_f32_e32 v120, 1.0, v120
	v_add_f32_e32 v121, 1.0, v121
	v_rcp_f32_e32 v120, v120
	v_rcp_f32_e32 v121, v121
	v_mul_f32_e32 v4, v4, v150
	v_mul_f32_e32 v0, v0, v96
	v_mul_f32_e32 v118, v118, v120
	v_mul_f32_e32 v119, v119, v121
	v_mul_f32_e32 v4, v4, v97
	v_mul_f32_e32 v0, v0, v118
	v_mul_f32_e32 v4, v4, v119
	v_cvt_pk_bf16_f32 v154, v0, v4
	v_lshlrev_b32_e32 v118, 16, v9
	v_and_b32_e32 v119, 0xffff0000, v9
	v_mul_f32_e32 v120, v125, v118
	v_mul_f32_e32 v121, v125, v119
	v_exp_f32_e32 v120, v120
	v_exp_f32_e32 v121, v121
	v_mul_f32_e32 v1, v1, v150
	v_add_f32_e32 v120, 1.0, v120
	v_add_f32_e32 v121, 1.0, v121
	v_rcp_f32_e32 v120, v120
	v_rcp_f32_e32 v121, v121
	v_mul_f32_e32 v5, v5, v150
	v_mul_f32_e32 v1, v1, v98
	v_mul_f32_e32 v118, v118, v120
	v_mul_f32_e32 v119, v119, v121
	v_mul_f32_e32 v5, v5, v99
	v_mul_f32_e32 v1, v1, v118
	v_mul_f32_e32 v5, v5, v119
	v_cvt_pk_bf16_f32 v155, v1, v5
	v_lshlrev_b32_e32 v118, 16, v10
	v_and_b32_e32 v119, 0xffff0000, v10
	v_mul_f32_e32 v120, v125, v118
	v_mul_f32_e32 v121, v125, v119
	v_exp_f32_e32 v120, v120
	v_exp_f32_e32 v121, v121
	v_mul_f32_e32 v2, v2, v150
	v_add_f32_e32 v120, 1.0, v120
	v_add_f32_e32 v121, 1.0, v121
	v_rcp_f32_e32 v120, v120
	v_rcp_f32_e32 v121, v121
	v_mul_f32_e32 v6, v6, v150
	v_mul_f32_e32 v2, v2, v100
	v_mul_f32_e32 v118, v118, v120
	v_mul_f32_e32 v119, v119, v121
	v_mul_f32_e32 v6, v6, v101
	v_mul_f32_e32 v2, v2, v118
	v_mul_f32_e32 v6, v6, v119
	v_cvt_pk_bf16_f32 v156, v2, v6
	v_lshlrev_b32_e32 v118, 16, v11
	v_and_b32_e32 v119, 0xffff0000, v11
	v_mul_f32_e32 v120, v125, v118
	v_mul_f32_e32 v121, v125, v119
	v_exp_f32_e32 v120, v120
	v_exp_f32_e32 v121, v121
	v_mul_f32_e32 v3, v3, v150
	v_add_f32_e32 v120, 1.0, v120
	v_add_f32_e32 v121, 1.0, v121
	v_rcp_f32_e32 v120, v120
	v_rcp_f32_e32 v121, v121
	v_mul_f32_e32 v7, v7, v150
	v_mul_f32_e32 v3, v3, v102
	v_mul_f32_e32 v118, v118, v120
	v_mul_f32_e32 v119, v119, v121
	v_mul_f32_e32 v7, v7, v103
	v_mul_f32_e32 v3, v3, v118
	v_mul_f32_e32 v7, v7, v119
	v_cvt_pk_bf16_f32 v157, v3, v7
	global_store_dwordx4 v107, v[154:157], s[42:43] sc1
	s_add_u32 s24, s24, s6
	s_branch .Lfin_done

; DI void unpack8(u32x4 v, float* o) { o[0] = lo16(v.x); o[1] = hi16(v.x); o[2] = lo16(v.y); o[3] = hi16(v.y); o[4] = lo16(v.z); o[5] = hi16(v.z); o[6] = lo16(v.w); o[7] = hi16(v.w); }
; DI u32x4 pack8(const float* o) { u32x4 r; r.x = pk2(o[0], o[1]); r.y = pk2(o[2], o[3]); r.z = pk2(o[4], o[5]); r.w = pk2(o[6], o[7]); return r; }
; DI float siluf(float x) { return x * __builtin_amdgcn_rcpf(1.f + __expf(-x)); }
; #define ITEM_BEGIN { size_t z_ = 0; asm volatile("" : "+s"(z_)); q.ws = p.ws + z_; sm = smem + osgpr(0); }
; #define PHASE_BEGIN P q = p; { size_t z_ = 0; asm volatile("" : "+s"(z_)); q.ws = p.ws + z_; } unsigned char* sm = smem + osgpr(0); const int b1 = osgpr(bid); (void)sm; (void)b1;
; DI void finish_item(const P& p, int l, int r16) {
;     ...
; #pragma unroll
;     for (int k = 0; k < 4; ++k) {
;         ra[k] = __builtin_nontemporal_load((const u32x4*)(O + ((size_t)(mx * 2 + 0) * NROW + row0 + k) * 512 + chn));
;         rb[k] = __builtin_nontemporal_load((const u32x4*)(O + ((size_t)(mx * 2 + 1) * NROW + row0 + k) * 512 + chn));
;         rg[k] = __builtin_nontemporal_load((const u32x4*)(S + (size_t)(row0 + k) * NP + (mx ? C_GDN_G : C_GLA_G) + chn));
;     }
;     const float* nwp = (mx ? p.gdn_norm : p.gla_norm) + l * 128 + 8 * sub;
;     const f32x4 nw0 = *(const f32x4*)nwp, nw1 = *(const f32x4*)(nwp + 4);
; #pragma unroll
;     for (int k = 0; k < 4; ++k) {
;         float a[8], b[8], o[8], gt[8];
;         unpack8(ra[k], a); unpack8(rb[k], b); unpack8(rg[k], gt);
;         float ss = 0.f;
; #pragma unroll
;         for (int e = 0; e < 8; ++e) { o[e] = a[e] + b[e]; ss += o[e] * o[e]; }
;         ss += __shfl_xor(ss, 1); ss += __shfl_xor(ss, 2); ss += __shfl_xor(ss, 4); ss += __shfl_xor(ss, 8);
;         const float rstd = rsqrtf(ss * (1.f / 128.f) + 1e-6f);
; #pragma unroll
;         for (int e = 0; e < 8; ++e) o[e] = o[e] * rstd * (e < 4 ? nw0[e & 3] : nw1[e & 3]) * siluf(gt[e]);
;         *(u32x4*)(Y + (size_t)(row0 + k) * DM + 512 * mx + chn) = pack8(o);
;     }
; }
; __global__ __launch_bounds__(512, 2) void mega(P p) {
;     ...
;         { PHASE_BEGIN const int nf = (l == 0 ? NROW : NLAT) / 16; for (int it = b1; it < nf; it += nb) { ITEM_BEGIN finish_item(q, l, it); } }
;         xcd_barrier(xb);
.Lfin_gloop:
	s_lshl_b32 s0, s24, 12
	s_add_u32 s36, s4, s0
	s_addc_u32 s37, s5, 0
	s_mul_i32 s0, s24, 0xe000
	s_add_u32 s38, s4, s0
	s_addc_u32 s39, s5, 0
	global_load_dwordx4 v[0:3], v104, s[36:37] nt
	global_load_dwordx4 v[4:7], v105, s[36:37] nt
	global_load_dwordx4 v[8:11], v106, s[38:39] nt
	s_waitcnt vmcnt(0)
	v_and_b32_e32 v118, 0xffff0000, v0
	v_and_b32_e32 v119, 0xffff0000, v4
	v_lshlrev_b32_e32 v0, 16, v0
	v_lshlrev_b32_e32 v120, 16, v4
	v_add_f32_e32 v0, v0, v120
	v_add_f32_e32 v4, v118, v119
	v_mul_f32_e32 v142, v0, v0
	v_fmac_f32_e32 v142, v4, v4
	v_and_b32_e32 v118, 0xffff0000, v1
	v_and_b32_e32 v119, 0xffff0000, v5
	v_lshlrev_b32_e32 v1, 16, v1
	v_lshlrev_b32_e32 v120, 16, v5
	v_add_f32_e32 v1, v1, v120
	v_add_f32_e32 v5, v118, v119
	v_fmac_f32_e32 v142, v1, v1
	v_fmac_f32_e32 v142, v5, v5
	v_and_b32_e32 v118, 0xffff0000, v2
	v_and_b32_e32 v119, 0xffff0000, v6
	v_lshlrev_b32_e32 v2, 16, v2
	v_lshlrev_b32_e32 v120, 16, v6
	v_add_f32_e32 v2, v2, v120
	v_add_f32_e32 v6, v118, v119
	v_fmac_f32_e32 v142, v2, v2
	v_fmac_f32_e32 v142, v6, v6
	v_and_b32_e32 v118, 0xffff0000, v3
	v_and_b32_e32 v119, 0xffff0000, v7
	v_lshlrev_b32_e32 v3, 16, v3
	v_lshlrev_b32_e32 v120, 16, v7
	v_add_f32_e32 v3, v3, v120
	v_add_f32_e32 v7, v118, v119
	v_fmac_f32_e32 v142, v3, v3
	v_fmac_f32_e32 v142, v7, v7
	s_nop 1
	v_add_f32_dpp v142, v142, v142 quad_perm:[1,0,3,2] row_mask:0xf bank_mask:0xf
	s_nop 1
	v_add_f32_dpp v142, v142, v142 quad_perm:[2,3,0,1] row_mask:0xf bank_mask:0xf
	s_nop 1
	v_add_f32_dpp v142, v142, v142 row_half_mirror row_mask:0xf bank_mask:0xf
	s_nop 1
	v_add_f32_dpp v142, v142, v142 row_mirror row_mask:0xf bank_mask:0xf
	v_fmamk_f32 v142, v142, 0x3c000000, v124
	v_rsq_f32_e32 v150, v142
	s_lshl_b32 s0, s24, 14
	s_add_u32 s42, s4, s0
	s_addc_u32 s43, s5, 0
	v_lshlrev_b32_e32 v118, 16, v8
	v_and_b32_e32 v119, 0xffff0000, v8
	v_mul_f32_e32 v120, v125, v118
	v_mul_f32_e32 v121, v125, v119
	v_exp_f32_e32 v120, v120
	v_exp_f32_e32 v121, v121
	v_mul_f32_e32 v0, v0, v150
	v_add_f32_e32 v120, 1.0, v120
	v_add_f32_e32 v121, 1.0, v121
	v_rcp_f32_e32 v120, v120
	v_rcp_f32_e32 v121, v121
	v_mul_f32_e32 v4, v4, v150
	v_mul_f32_e32 v0, v0, v96
	v_mul_f32_e32 v118, v118, v120
	v_mul_f32_e32 v119, v119, v121
	v_mul_f32_e32 v4, v4, v97
	v_mul_f32_e32 v0, v0, v118
	v_mul_f32_e32 v4, v4, v119
	v_cvt_pk_bf16_f32 v154, v0, v4
	v_lshlrev_b32_e32 v118, 16, v9
	v_and_b32_e32 v119, 0xffff0000, v9
	v_mul_f32_e32 v120, v125, v118
	v_mul_f32_e32 v121, v125, v119
	v_exp_f32_e32 v120, v120
	v_exp_f32_e32 v121, v121
	v_mul_f32_e32 v1, v1, v150
	v_add_f32_e32 v120, 1.0, v120
	v_add_f32_e32 v121, 1.0, v121
	v_rcp_f32_e32 v120, v120
	v_rcp_f32_e32 v121, v121
	v_mul_f32_e32 v5, v5, v150
	v_mul_f32_e32 v1, v1, v98
	v_mul_f32_e32 v118, v118, v120
	v_mul_f32_e32 v119, v119, v121
	v_mul_f32_e32 v5, v5, v99
	v_mul_f32_e32 v1, v1, v118
	v_mul_f32_e32 v5, v5, v119
	v_cvt_pk_bf16_f32 v155, v1, v5
	v_lshlrev_b32_e32 v118, 16, v10
	v_and_b32_e32 v119, 0xffff0000, v10
	v_mul_f32_e32 v120, v125, v118
	v_mul_f32_e32 v121, v125, v119
	v_exp_f32_e32 v120, v120
	v_exp_f32_e32 v121, v121
	v_mul_f32_e32 v2, v2, v150
	v_add_f32_e32 v120, 1.0, v120
	v_add_f32_e32 v121, 1.0, v121
	v_rcp_f32_e32 v120, v120
	v_rcp_f32_e32 v121, v121
	v_mul_f32_e32 v6, v6, v150
	v_mul_f32_e32 v2, v2, v100
	v_mul_f32_e32 v118, v118, v120
	v_mul_f32_e32 v119, v119, v121
	v_mul_f32_e32 v6, v6, v101
	v_mul_f32_e32 v2, v2, v118
	v_mul_f32_e32 v6, v6, v119
	v_cvt_pk_bf16_f32 v156, v2, v6
	v_lshlrev_b32_e32 v118, 16, v11
	v_and_b32_e32 v119, 0xffff0000, v11
	v_mul_f32_e32 v120, v125, v118
	v_mul_f32_e32 v121, v125, v119
	v_exp_f32_e32 v120, v120
	v_exp_f32_e32 v121, v121
	v_mul_f32_e32 v3, v3, v150
	v_add_f32_e32 v120, 1.0, v120
	v_add_f32_e32 v121, 1.0, v121
	v_rcp_f32_e32 v120, v120
	v_rcp_f32_e32 v121, v121
	v_mul_f32_e32 v7, v7, v150
	v_mul_f32_e32 v3, v3, v102
	v_mul_f32_e32 v118, v118, v120
	v_mul_f32_e32 v119, v119, v121
	v_mul_f32_e32 v7, v7, v103
	v_mul_f32_e32 v3, v3, v118
	v_mul_f32_e32 v7, v7, v119
	v_cvt_pk_bf16_f32 v157, v3, v7
	global_store_dwordx4 v107, v[154:157], s[42:43] sc1
	s_add_u32 s24, s24, s6
	s_cmp_lt_u32 s24, s10
	s_cbranch_scc1 .Lfin_gloop
.Lfin_done:
	s_setprio 0
.LBB0_682:
	s_waitcnt vmcnt(0)
	s_barrier
	s_mov_b64 s[0:1], exec
	v_readlane_b32 s2, v253, 1
	v_readlane_b32 s3, v253, 2
	s_and_b64 s[2:3], s[0:1], s[2:3]
	s_mov_b64 s[8:9], 0x6c3c000
	s_mov_b64 exec, s[2:3]
	s_cbranch_execz .LBB0_730
	v_readlane_b32 s2, v254, 32
	s_waitcnt vmcnt(0) expcnt(0) lgkmcnt(0)
	s_nop 0
	v_mov_b32_e32 v0, s2
	ds_read_b32 v2, v0
	v_readlane_b32 s2, v254, 33
	s_waitcnt lgkmcnt(0)
	v_cmp_ne_u32_e32 vcc, 0, v2
	v_mov_b32_e32 v0, s2
	ds_read_b32 v0, v0
	s_cbranch_vccnz .LBB0_698
	s_mov_b32 s2, 1
	s_branch .LBB0_686

; DI float lo16(unsigned u) { return __uint_as_float(u << 16); }
; DI float hi16(unsigned u) { return __uint_as_float(u & 0xFFFF0000u); }
; DI int otid() { int t = threadIdx.x; asm volatile("" : "+v"(t)); return t; }
; DI int osgpr(int v) { asm volatile("" : "+s"(v)); return v; }
; #define PHASE_BEGIN P q = p; { size_t z_ = 0; asm volatile("" : "+s"(z_)); q.ws = p.ws + z_; } unsigned char* sm = smem + osgpr(0); const int b1 = osgpr(bid); (void)sm; (void)b1;
; DI void post_phase(const P& p, int l, unsigned char* smem, int t0, int t1, int bstart, int bstride) {
;     const int tid = otid(); const int wave = tid >> 6, lane = tid & 63;
;     const float* mod = (const float*)(p.ws + WS_MOD);
;     bf16_t* nb = (bf16_t*)(p.ws + WS_NBUF);
;     const bf16_t* yo = (const bf16_t*)(p.ws + WS_SBUF);
;     float* hc = (float*)(p.ws + WS_HC);
;     for (int rt = t0 + osgpr(bstart); rt < t1; rt += bstride) {
;       for (int rr = 0; rr < 2; ++rr) {
;         const int row = rt * 16 + wave * 2 + rr;
;         const int mr = row < NLAT ? (row >> 11) : 4;
;         const float* h = l == 0 ? (row < NLAT ? p.x + (size_t)row * DM : p.ctx + (size_t)(row - NLAT) * DM) : p.out + (size_t)row * DM;
;         float* hdst = row < NLAT ? p.out + (size_t)row * DM : hc + (size_t)(row - NLAT) * DM;
;         f32x4 y[8]; float ss = 0.f;
; #pragma unroll
;         for (int i = 0; i < 8; ++i) {
;             const u32x2 w = __builtin_nontemporal_load((const u32x2*)(yo + (size_t)row * DM + i * 256 + lane * 4));
;             y[i] = (f32x4){lo16(w.x), hi16(w.x), lo16(w.y), hi16(w.y)};
;             ss += y[i][0] * y[i][0] + y[i][1] * y[i][1] + y[i][2] * y[i][2] + y[i][3] * y[i][3];
;         }
;         ss = wave_sum(ss);
;         const float rstd = rsqrtf(ss * (1.f / 2048.f) + 1e-6f);
; __global__ __launch_bounds__(512, 2) void mega(P p) {
;     ...
;             PHASE_BEGIN post_phase(q, 1, sm, 0, NLAT / 16, b1, nb);
.LBB0_799:
	s_or_b64 exec, exec, s[0:1]
	v_readlane_b32 s2, v254, 63
	v_readlane_b32 s3, v252, 0
	s_mov_b64 s[0:1], -1
	s_and_b64 vcc, exec, s[2:3]
	s_waitcnt lgkmcnt(0)
	s_barrier
	s_cbranch_vccz .LBB0_806
	s_mov_b64 s[0:1], 0
	s_mov_b32 s2, s19
	v_mov_b32_e32 v0, v166
	v_readlane_b32 s2, v253, 0
	s_nop 0
	s_cmpk_gt_i32 s2, 0x1ff
	s_cbranch_scc1 .LBB0_805
	v_readfirstlane_b32 s98, v166
	s_nop 0
	s_lshr_b32 s98, s98, 6
	s_cmp_ge_u32 s98, 4
	s_cbranch_scc0 .Lp1_prio_done
	s_setprio 1
.Lp1_prio_done:
	v_readlane_b32 s4, v254, 26
	v_readlane_b32 s5, v254, 27
	v_readlane_b32 s6, v254, 37
	v_readlane_b32 s7, v254, 38
	v_readlane_b32 s8, v254, 18
	v_readlane_b32 s9, v254, 19
	v_readlane_b32 s10, v254, 28
	v_and_b32_e32 v18, 63, v166
	v_lshrrev_b32_e32 v19, 6, v166
	v_lshlrev_b32_e32 v0, 4, v18
	v_lshlrev_b32_e32 v2, 3, v18
	v_readfirstlane_b32 s11, v19
	v_add_u32_e32 v1, 0x1000, v0
	v_add_u32_e32 v17, 0x1000, v2
	v_xor_b32_e32 v3, 32, v18
	v_xor_b32_e32 v4, 16, v18
	v_xor_b32_e32 v5, 8, v18
	v_xor_b32_e32 v6, 4, v18
	v_xor_b32_e32 v7, 2, v18
	v_xor_b32_e32 v8, 1, v18
	v_lshlrev_b32_e32 v3, 2, v3
	v_lshlrev_b32_e32 v4, 2, v4
	v_lshlrev_b32_e32 v5, 2, v5
	v_lshlrev_b32_e32 v6, 2, v6
	v_lshlrev_b32_e32 v7, 2, v7
	v_lshlrev_b32_e32 v8, 2, v8
	s_lshl_b32 s11, s11, 1
	global_load_dwordx4 v[20:23], v0, s[8:9] offset:0
	global_load_dwordx4 v[24:27], v0, s[8:9] offset:1024
	global_load_dwordx4 v[28:31], v0, s[8:9] offset:2048
	global_load_dwordx4 v[32:35], v0, s[8:9] offset:3072
	global_load_dwordx4 v[36:39], v1, s[8:9] offset:0
	global_load_dwordx4 v[40:43], v1, s[8:9] offset:1024
	global_load_dwordx4 v[44:47], v1, s[8:9] offset:2048
	global_load_dwordx4 v[48:51], v1, s[8:9] offset:3072

; #define PHASE_BEGIN P q = p; { size_t z_ = 0; asm volatile("" : "+s"(z_)); q.ws = p.ws + z_; } unsigned char* sm = smem + osgpr(0); const int b1 = osgpr(bid); (void)sm; (void)b1;
; __global__ __launch_bounds__(512, 2) void mega(P p) {
;     ...
;             PHASE_BEGIN post_phase(q, 1, sm, 0, NLAT / 16, b1, nb);
.LBB0_805:
	s_setprio 0
	s_mov_b64 s[0:1], 0
